# FFN1 gate/up epilogue: the in-place packed x+0.0 adds left over from the disabled LayerNorm fold removed
# baseline (speedup 1.0000x reference)
; __device__ __forceinline__ unsigned cvt_pk_bf16(float lo, float hi) { unsigned r; asm volatile("v_cvt_pk_bf16_f32 %0, %1, %2" : "=v"(r) : "v"(lo), "v"(hi)); return r; }
; __device__ __forceinline__ float siluf_(float x) { return x * sigmoidf_(x); }
; __device__ __forceinline__ f32x2 ln_stats(f32x2 sm) { const float mu = sm[0] * (1.f / D); const float var = fmaxf(sm[1] * (1.f / D) - mu * mu, 0.f); return (f32x2){mu, 1.0f / sqrtf(var + LN_EPS)}; }
;     __device__ __forceinline__ void operator()(const f32x4 (&acc)[2][2][4][2], const Unit& u, int wr, int wc, int fr, int fq) const {
;         const int row0 = u.pm * BM + wr * 64 + fr, col0 = u.pn * HALF + wc * 32 + 8 * fq;
;         f32x4 s1[2][2], s2[2][2];
; #pragma unroll
;         for (int bj = 0; bj < 2; ++bj)
; #pragma unroll
;             for (int n = 0; n < 2; ++n) { s1[bj][n] = (f32x4){0.f, 0.f, 0.f, 0.f}; s2[bj][n] = s1[bj][n];
;                 if (rsum) { const int ci = u.pn * BM + bj * HALF + wc * 32 + 8 * fq + 4 * n; s1[bj][n] = *(const f32x4*)(cs + ci); s2[bj][n] = *(const f32x4*)(cs + NZ + ci); } }
; #pragma unroll
;         for (int ai = 0; ai < 2; ++ai)
; #pragma unroll
;             for (int m = 0; m < 4; ++m) {
;                 const int r = row0 + ai * HALF + m * 16;
;                 bf16_t* rowp = H + (size_t)r * ldh + col0;
;                 f32x2 st = (f32x2){0.f, 1.f};
;                 if (rsum) st = ln_stats(*(const f32x2*)(rsum + 2 * (size_t)r));
;                 f32x4 v0, v1;
; #pragma unroll
;                 for (int j = 0; j < 4; ++j) {
;                     const float g0 = st[1] * (acc[ai][0][m][0][j] - st[0] * s1[0][0][j]) + s2[0][0][j], u0 = st[1] * (acc[ai][1][m][0][j] - st[0] * s1[1][0][j]) + s2[1][0][j];
;                     const float g1 = st[1] * (acc[ai][0][m][1][j] - st[0] * s1[0][1][j]) + s2[0][1][j], u1 = st[1] * (acc[ai][1][m][1][j] - st[0] * s1[1][1][j]) + s2[1][1][j];
;                     v0[j] = siluf_(g0) * u0; v1[j] = siluf_(g1) * u1;
;                 }
;                 u32x4 w; w.x = cvt_pk_bf16(v0[0], v0[1]); w.y = cvt_pk_bf16(v0[2], v0[3]); w.z = cvt_pk_bf16(v1[0], v1[1]); w.w = cvt_pk_bf16(v1[2], v1[3]);
;                 *(u32x4*)rowp = w;
.LBB0_158:
	v_mov_b32_e32 v154, v124
	v_mov_b32_e32 v155, v116
	v_mov_b32_e32 v156, v120
	v_mul_f32_e32 v116, 0xbfb8aa3b, v154
	v_exp_f32_e32 v116, v116
	v_mov_b32_e32 v157, v112
	v_lshl_or_b32 v140, s53, 7, v146
	v_add_f32_e32 v112, 1.0, v116
	v_rcp_f32_e32 v112, v112
	v_mul_f32_e32 v116, 0xbfb8aa3b, v156
	v_exp_f32_e32 v116, v116
	v_lshl_add_u32 v150, s18, 8, v144
	v_mul_f32_e32 v112, v154, v112
	v_mul_f32_e32 v124, v112, v155
	v_add_f32_e32 v112, 1.0, v116
	v_mov_b32_e32 v116, v125
	v_rcp_f32_e32 v120, v112
	v_mov_b32_e32 v112, v121
	v_mul_f32_e32 v121, 0xbfb8aa3b, v116
	v_exp_f32_e32 v121, v121
	v_mul_f32_e32 v120, v156, v120
	v_mul_f32_e32 v125, 0xbfb8aa3b, v112
	v_add_f32_e32 v121, 1.0, v121
	v_rcp_f32_e32 v121, v121
	v_exp_f32_e32 v125, v125
	v_mul_f32_e32 v151, v120, v157
	v_mov_b32_e32 v120, v122
	v_mul_f32_e32 v116, v116, v121
	v_mul_f32_e32 v154, v116, v117
	v_mov_b32_e32 v116, v126
	v_mov_b32_e32 v117, v118
	v_add_f32_e32 v125, 1.0, v125
	v_mul_f32_e32 v118, 0xbfb8aa3b, v116
	v_exp_f32_e32 v118, v118
	v_mov_b32_e32 v121, v114
	v_rcp_f32_e32 v125, v125
	v_add_f32_e32 v114, 1.0, v118
	v_rcp_f32_e32 v114, v114
	v_mul_f32_e32 v118, 0xbfb8aa3b, v120
	v_exp_f32_e32 v118, v118
	v_mul_f32_e32 v112, v112, v125
	v_mul_f32_e32 v122, v112, v113
	v_mul_f32_e32 v112, v116, v114
	v_mul_f32_e32 v116, v112, v117
	v_add_f32_e32 v112, 1.0, v118
	v_mov_b32_e32 v118, v127
	v_rcp_f32_e32 v117, v112
	v_pk_add_f32 v[112:113], v[118:119], 0 op_sel_hi:[1,0]
	v_mov_b32_e32 v114, v123
	v_mul_f32_e32 v118, 0xbfb8aa3b, v112
	v_exp_f32_e32 v118, v118
	v_mul_f32_e32 v119, 0xbfb8aa3b, v114
	v_exp_f32_e32 v119, v119
	v_ashrrev_i32_e32 v141, 31, v140
	v_add_f32_e32 v118, 1.0, v118
	v_rcp_f32_e32 v118, v118
	v_add_f32_e32 v119, 1.0, v119
	v_rcp_f32_e32 v119, v119
	v_mov_b64_e32 v[142:143], s[40:41]
	v_mul_f32_e32 v112, v112, v118
	v_mul_f32_e32 v113, v112, v113
	v_mul_f32_e32 v112, v114, v119
	v_mad_i64_i32 v[152:153], s[20:21], v150, s51, v[142:143]
	v_lshlrev_b64 v[140:141], 1, v[140:141]
	v_mul_f32_e32 v117, v120, v117
	v_mul_f32_e32 v115, v112, v115
	v_lshl_add_u64 v[152:153], v[152:153], 0, v[140:141]
	v_mul_f32_e32 v117, v117, v121
	v_cvt_pk_bf16_f32 v112, v124, v154
	v_cvt_pk_bf16_f32 v113, v116, v113
	v_cvt_pk_bf16_f32 v114, v151, v122
	v_cvt_pk_bf16_f32 v115, v117, v115
	global_store_dwordx4 v[152:153], v[112:115], off
	v_mov_b32_e32 v116, v104
	v_mov_b32_e32 v117, v96
	v_mov_b32_e32 v114, v108
	v_mov_b32_e32 v115, v100
	v_mul_f32_e32 v100, 0xbfb8aa3b, v114
	v_exp_f32_e32 v100, v100
	v_or_b32_e32 v112, 16, v150
	v_mad_i64_i32 v[112:113], s[20:21], v112, s51, v[142:143]
	v_add_f32_e32 v96, 1.0, v100
	v_rcp_f32_e32 v96, v96
	v_mul_f32_e32 v100, 0xbfb8aa3b, v116
	v_exp_f32_e32 v100, v100
	v_lshl_add_u64 v[112:113], v[112:113], 0, v[140:141]
	v_mul_f32_e32 v96, v114, v96
	v_mul_f32_e32 v108, v96, v115
	v_add_f32_e32 v96, 1.0, v100
	v_mov_b32_e32 v100, v109
	v_rcp_f32_e32 v104, v96
	v_mov_b32_e32 v96, v105
	v_mul_f32_e32 v105, 0xbfb8aa3b, v100
	v_exp_f32_e32 v105, v105
	v_mul_f32_e32 v104, v116, v104
	v_mul_f32_e32 v109, 0xbfb8aa3b, v96
	v_add_f32_e32 v105, 1.0, v105
	v_rcp_f32_e32 v105, v105
	v_exp_f32_e32 v109, v109
	v_mul_f32_e32 v114, v104, v117
	v_mov_b32_e32 v104, v106
	v_mul_f32_e32 v100, v100, v105
	v_mul_f32_e32 v115, v100, v101
	v_mov_b32_e32 v100, v110
	v_mov_b32_e32 v101, v102
	v_add_f32_e32 v109, 1.0, v109
	v_mul_f32_e32 v102, 0xbfb8aa3b, v100
	v_exp_f32_e32 v102, v102
	v_mov_b32_e32 v105, v98
	v_rcp_f32_e32 v109, v109
	v_add_f32_e32 v98, 1.0, v102
	v_rcp_f32_e32 v98, v98
	v_mul_f32_e32 v102, 0xbfb8aa3b, v104
	v_exp_f32_e32 v102, v102
	v_mul_f32_e32 v96, v96, v109
	v_mul_f32_e32 v106, v96, v97
	v_mul_f32_e32 v96, v100, v98
	v_mul_f32_e32 v100, v96, v101
	v_add_f32_e32 v96, 1.0, v102
	v_mov_b32_e32 v102, v111
	v_rcp_f32_e32 v101, v96
	v_pk_add_f32 v[96:97], v[102:103], 0 op_sel_hi:[1,0]
	v_mov_b32_e32 v98, v107
	v_mul_f32_e32 v102, 0xbfb8aa3b, v96
	v_exp_f32_e32 v102, v102
	v_mul_f32_e32 v103, 0xbfb8aa3b, v98
	v_exp_f32_e32 v103, v103
	v_mul_f32_e32 v101, v104, v101
	v_add_f32_e32 v102, 1.0, v102
	v_rcp_f32_e32 v102, v102
	v_add_f32_e32 v103, 1.0, v103
	v_rcp_f32_e32 v103, v103
	v_mul_f32_e32 v101, v101, v105
	v_mul_f32_e32 v96, v96, v102
	v_mul_f32_e32 v97, v96, v97
	v_mul_f32_e32 v96, v98, v103
	v_mul_f32_e32 v99, v96, v99
	v_cvt_pk_bf16_f32 v96, v108, v115
	v_cvt_pk_bf16_f32 v97, v100, v97
	v_cvt_pk_bf16_f32 v98, v114, v106
	v_cvt_pk_bf16_f32 v99, v101, v99
	global_store_dwordx4 v[112:113], v[96:99], off
	v_mov_b32_e32 v100, v88
	v_mov_b32_e32 v101, v80
	v_mov_b32_e32 v98, v92
	v_mov_b32_e32 v99, v84
	v_mul_f32_e32 v84, 0xbfb8aa3b, v98
	v_exp_f32_e32 v84, v84
	v_or_b32_e32 v96, 32, v150
	v_mad_i64_i32 v[96:97], s[20:21], v96, s51, v[142:143]
	v_add_f32_e32 v80, 1.0, v84
	v_rcp_f32_e32 v80, v80
	v_mul_f32_e32 v84, 0xbfb8aa3b, v100
	v_exp_f32_e32 v84, v84
	v_lshl_add_u64 v[96:97], v[96:97], 0, v[140:141]
	v_mul_f32_e32 v80, v98, v80
	v_mul_f32_e32 v92, v80, v99
	v_add_f32_e32 v80, 1.0, v84
	v_mov_b32_e32 v84, v93
	v_rcp_f32_e32 v88, v80
	v_mov_b32_e32 v80, v89
	v_mul_f32_e32 v89, 0xbfb8aa3b, v84
	v_exp_f32_e32 v89, v89
	v_mul_f32_e32 v88, v100, v88
	v_mul_f32_e32 v93, 0xbfb8aa3b, v80
	v_add_f32_e32 v89, 1.0, v89
	v_rcp_f32_e32 v89, v89
	v_exp_f32_e32 v93, v93
	v_mul_f32_e32 v98, v88, v101
	v_mov_b32_e32 v88, v90
	v_mul_f32_e32 v84, v84, v89
	v_mul_f32_e32 v99, v84, v85
	v_mov_b32_e32 v84, v94
	v_mov_b32_e32 v85, v86
	v_add_f32_e32 v93, 1.0, v93
	v_mul_f32_e32 v86, 0xbfb8aa3b, v84
	v_exp_f32_e32 v86, v86
	v_mov_b32_e32 v89, v82
	v_rcp_f32_e32 v93, v93
	v_add_f32_e32 v82, 1.0, v86
	v_rcp_f32_e32 v82, v82
	v_mul_f32_e32 v86, 0xbfb8aa3b, v88
; __device__ __forceinline__ unsigned cvt_pk_bf16(float lo, float hi) { unsigned r; asm volatile("v_cvt_pk_bf16_f32 %0, %1, %2" : "=v"(r) : "v"(lo), "v"(hi)); return r; }
; __device__ __forceinline__ float siluf_(float x) { return x * sigmoidf_(x); }
; __device__ __forceinline__ f32x2 ln_stats(f32x2 sm) { const float mu = sm[0] * (1.f / D); const float var = fmaxf(sm[1] * (1.f / D) - mu * mu, 0.f); return (f32x2){mu, 1.0f / sqrtf(var + LN_EPS)}; }
;     __device__ __forceinline__ void operator()(const f32x4 (&acc)[2][2][4][2], const Unit& u, int wr, int wc, int fr, int fq) const {
;     ...
;                 const int r = row0 + ai * HALF + m * 16;
;                 bf16_t* rowp = H + (size_t)r * ldh + col0;
;                 f32x2 st = (f32x2){0.f, 1.f};
;                 if (rsum) st = ln_stats(*(const f32x2*)(rsum + 2 * (size_t)r));
;                 f32x4 v0, v1;
; #pragma unroll
;                 for (int j = 0; j < 4; ++j) {
;                     const float g0 = st[1] * (acc[ai][0][m][0][j] - st[0] * s1[0][0][j]) + s2[0][0][j], u0 = st[1] * (acc[ai][1][m][0][j] - st[0] * s1[1][0][j]) + s2[1][0][j];
;                     const float g1 = st[1] * (acc[ai][0][m][1][j] - st[0] * s1[0][1][j]) + s2[0][1][j], u1 = st[1] * (acc[ai][1][m][1][j] - st[0] * s1[1][1][j]) + s2[1][1][j];
;                     v0[j] = siluf_(g0) * u0; v1[j] = siluf_(g1) * u1;
;                 }
;                 u32x4 w; w.x = cvt_pk_bf16(v0[0], v0[1]); w.y = cvt_pk_bf16(v0[2], v0[3]); w.z = cvt_pk_bf16(v1[0], v1[1]); w.w = cvt_pk_bf16(v1[2], v1[3]);
;                 *(u32x4*)rowp = w;
	v_exp_f32_e32 v86, v86
	v_mul_f32_e32 v80, v80, v93
	v_mul_f32_e32 v90, v80, v81
	v_mul_f32_e32 v80, v84, v82
	v_mul_f32_e32 v84, v80, v85
	v_add_f32_e32 v80, 1.0, v86
	v_mov_b32_e32 v86, v95
	v_rcp_f32_e32 v85, v80
	v_pk_add_f32 v[80:81], v[86:87], 0 op_sel_hi:[1,0]
	v_mov_b32_e32 v82, v91
	v_mul_f32_e32 v86, 0xbfb8aa3b, v80
	v_exp_f32_e32 v86, v86
	v_mul_f32_e32 v87, 0xbfb8aa3b, v82
	v_exp_f32_e32 v87, v87
	v_mul_f32_e32 v85, v88, v85
	v_add_f32_e32 v86, 1.0, v86
	v_rcp_f32_e32 v86, v86
	v_add_f32_e32 v87, 1.0, v87
	v_rcp_f32_e32 v87, v87
	v_mul_f32_e32 v85, v85, v89
	v_mul_f32_e32 v80, v80, v86
	v_mul_f32_e32 v81, v80, v81
	v_mul_f32_e32 v80, v82, v87
	v_mul_f32_e32 v83, v80, v83
	v_cvt_pk_bf16_f32 v80, v92, v99
	v_cvt_pk_bf16_f32 v81, v84, v81
	v_cvt_pk_bf16_f32 v82, v98, v90
	v_cvt_pk_bf16_f32 v83, v85, v83
	global_store_dwordx4 v[96:97], v[80:83], off
	v_mov_b32_e32 v84, v72
	v_mov_b32_e32 v85, v64
	v_mov_b32_e32 v82, v76
	v_mov_b32_e32 v83, v68
	v_mul_f32_e32 v68, 0xbfb8aa3b, v82
	v_exp_f32_e32 v68, v68
	v_or_b32_e32 v80, 48, v150
	v_mad_i64_i32 v[80:81], s[20:21], v80, s51, v[142:143]
	v_add_f32_e32 v64, 1.0, v68
	v_rcp_f32_e32 v64, v64
	v_mul_f32_e32 v68, 0xbfb8aa3b, v84
	v_exp_f32_e32 v68, v68
	v_lshl_add_u64 v[80:81], v[80:81], 0, v[140:141]
	v_mul_f32_e32 v64, v82, v64
	v_mul_f32_e32 v76, v64, v83
	v_add_f32_e32 v64, 1.0, v68
	v_mov_b32_e32 v68, v77
	v_rcp_f32_e32 v72, v64
	v_mov_b32_e32 v64, v73
	v_mul_f32_e32 v73, 0xbfb8aa3b, v68
	v_exp_f32_e32 v73, v73
	v_mul_f32_e32 v72, v84, v72
	v_mul_f32_e32 v77, 0xbfb8aa3b, v64
	v_add_f32_e32 v73, 1.0, v73
	v_rcp_f32_e32 v73, v73
	v_exp_f32_e32 v77, v77
	v_mul_f32_e32 v82, v72, v85
	v_mov_b32_e32 v72, v74
	v_mul_f32_e32 v68, v68, v73
	v_mul_f32_e32 v83, v68, v69
	v_mov_b32_e32 v68, v78
	v_mov_b32_e32 v69, v70
	v_add_f32_e32 v77, 1.0, v77
	v_mul_f32_e32 v70, 0xbfb8aa3b, v68
	v_exp_f32_e32 v70, v70
	v_mov_b32_e32 v73, v66
	v_rcp_f32_e32 v77, v77
	v_add_f32_e32 v66, 1.0, v70
	v_rcp_f32_e32 v66, v66
	v_mul_f32_e32 v70, 0xbfb8aa3b, v72
	v_exp_f32_e32 v70, v70
	v_mul_f32_e32 v64, v64, v77
	v_mul_f32_e32 v74, v64, v65
	v_mul_f32_e32 v64, v68, v66
	v_mul_f32_e32 v68, v64, v69
	v_add_f32_e32 v64, 1.0, v70
	v_mov_b32_e32 v70, v79
	v_rcp_f32_e32 v69, v64
	v_pk_add_f32 v[64:65], v[70:71], 0 op_sel_hi:[1,0]
	v_mov_b32_e32 v66, v75
	v_mul_f32_e32 v70, 0xbfb8aa3b, v64
	v_exp_f32_e32 v70, v70
	v_mul_f32_e32 v71, 0xbfb8aa3b, v66
	v_exp_f32_e32 v71, v71
	v_mul_f32_e32 v69, v72, v69
	v_add_f32_e32 v70, 1.0, v70
	v_rcp_f32_e32 v70, v70
	v_add_f32_e32 v71, 1.0, v71
	v_rcp_f32_e32 v71, v71
	v_mul_f32_e32 v69, v69, v73
	v_mul_f32_e32 v64, v64, v70
	v_mul_f32_e32 v65, v64, v65
	v_mul_f32_e32 v64, v66, v71
	v_mul_f32_e32 v67, v64, v67
	v_cvt_pk_bf16_f32 v64, v76, v83
	v_cvt_pk_bf16_f32 v65, v68, v65
	v_cvt_pk_bf16_f32 v66, v82, v74
	v_cvt_pk_bf16_f32 v67, v69, v67
	global_store_dwordx4 v[80:81], v[64:67], off
	v_mov_b32_e32 v68, v56
	v_mov_b32_e32 v69, v48
	v_mov_b32_e32 v66, v60
	v_mov_b32_e32 v67, v52
	v_mul_f32_e32 v52, 0xbfb8aa3b, v66
	v_exp_f32_e32 v52, v52
	v_add_u32_e32 v64, 0x80, v150
	v_mad_i64_i32 v[64:65], s[20:21], v64, s51, v[142:143]
	v_add_f32_e32 v48, 1.0, v52
	v_rcp_f32_e32 v48, v48
	v_mul_f32_e32 v52, 0xbfb8aa3b, v68
	v_exp_f32_e32 v52, v52
	v_lshl_add_u64 v[64:65], v[64:65], 0, v[140:141]
	v_mul_f32_e32 v48, v66, v48
	v_mul_f32_e32 v60, v48, v67
	v_add_f32_e32 v48, 1.0, v52
	v_mov_b32_e32 v52, v61
	v_rcp_f32_e32 v56, v48
	v_mov_b32_e32 v48, v57
	v_mul_f32_e32 v57, 0xbfb8aa3b, v52
	v_exp_f32_e32 v57, v57
	v_mul_f32_e32 v56, v68, v56
	v_mul_f32_e32 v61, 0xbfb8aa3b, v48
	v_add_f32_e32 v57, 1.0, v57
	v_rcp_f32_e32 v57, v57
	v_exp_f32_e32 v61, v61
	v_mul_f32_e32 v66, v56, v69
	v_mov_b32_e32 v56, v58
	v_mul_f32_e32 v52, v52, v57
	v_mul_f32_e32 v67, v52, v53
	v_mov_b32_e32 v52, v62
	v_mov_b32_e32 v53, v54
	v_add_f32_e32 v61, 1.0, v61
	v_mul_f32_e32 v54, 0xbfb8aa3b, v52
	v_exp_f32_e32 v54, v54
	v_mov_b32_e32 v57, v50
	v_rcp_f32_e32 v61, v61
	v_add_f32_e32 v50, 1.0, v54
	v_rcp_f32_e32 v50, v50
	v_mul_f32_e32 v54, 0xbfb8aa3b, v56
	v_exp_f32_e32 v54, v54
	v_mul_f32_e32 v48, v48, v61
	v_mul_f32_e32 v58, v48, v49
	v_mul_f32_e32 v48, v52, v50
	v_mul_f32_e32 v52, v48, v53
	v_add_f32_e32 v48, 1.0, v54
	v_mov_b32_e32 v54, v63
	v_rcp_f32_e32 v53, v48
	v_pk_add_f32 v[48:49], v[54:55], 0 op_sel_hi:[1,0]
	v_mov_b32_e32 v50, v59
	v_mul_f32_e32 v54, 0xbfb8aa3b, v48
	v_exp_f32_e32 v54, v54
	v_mul_f32_e32 v55, 0xbfb8aa3b, v50
	v_exp_f32_e32 v55, v55
	v_mul_f32_e32 v53, v56, v53
	v_add_f32_e32 v54, 1.0, v54
	v_rcp_f32_e32 v54, v54
	v_add_f32_e32 v55, 1.0, v55
	v_rcp_f32_e32 v55, v55
	v_mul_f32_e32 v53, v53, v57
	v_mul_f32_e32 v48, v48, v54
	v_mul_f32_e32 v49, v48, v49
	v_mul_f32_e32 v48, v50, v55
	v_mul_f32_e32 v51, v48, v51
	v_cvt_pk_bf16_f32 v48, v60, v67
	v_cvt_pk_bf16_f32 v49, v52, v49
	v_cvt_pk_bf16_f32 v50, v66, v58
	v_cvt_pk_bf16_f32 v51, v53, v51
	global_store_dwordx4 v[64:65], v[48:51], off
	v_mov_b32_e32 v52, v40
	v_mov_b32_e32 v53, v32
	v_mov_b32_e32 v50, v44
	v_mov_b32_e32 v51, v36
	v_mul_f32_e32 v36, 0xbfb8aa3b, v50
	v_exp_f32_e32 v36, v36
	v_add_u32_e32 v48, 0x90, v150
	v_mad_i64_i32 v[48:49], s[20:21], v48, s51, v[142:143]
	v_add_f32_e32 v32, 1.0, v36
	v_rcp_f32_e32 v32, v32
	v_mul_f32_e32 v36, 0xbfb8aa3b, v52
	v_exp_f32_e32 v36, v36
	v_lshl_add_u64 v[48:49], v[48:49], 0, v[140:141]
	v_mul_f32_e32 v32, v50, v32
	v_mul_f32_e32 v44, v32, v51
	v_add_f32_e32 v32, 1.0, v36
	v_mov_b32_e32 v36, v45
	v_rcp_f32_e32 v40, v32
	v_mov_b32_e32 v32, v41
	v_mul_f32_e32 v41, 0xbfb8aa3b, v36
; __device__ __forceinline__ unsigned cvt_pk_bf16(float lo, float hi) { unsigned r; asm volatile("v_cvt_pk_bf16_f32 %0, %1, %2" : "=v"(r) : "v"(lo), "v"(hi)); return r; }
; __device__ __forceinline__ float siluf_(float x) { return x * sigmoidf_(x); }
; __device__ __forceinline__ f32x2 ln_stats(f32x2 sm) { const float mu = sm[0] * (1.f / D); const float var = fmaxf(sm[1] * (1.f / D) - mu * mu, 0.f); return (f32x2){mu, 1.0f / sqrtf(var + LN_EPS)}; }
; #define PG8_BAR __builtin_amdgcn_s_barrier()
; template <class Sched, class Epi, bool ALIGN_EPI, bool SP2>
; __device__ __forceinline__ void gemm_phase(LAS unsigned char* lds, const int K, const int lda, const int ldb, const Sched& S, const Epi& E) {
;     ...
;         if (!has_next) break;
;         bool keep = false;
;         if constexpr (Epi::CAN_KEEP) keep = (cur.kind < 2);
;         if (!keep) {
; #pragma unroll
;         for (int a = 0; a < 2; ++a)
; #pragma unroll
;             for (int b = 0; b < 2; ++b)
; #pragma unroll
;                 for (int m = 0; m < 4; ++m)
; #pragma unroll
;                     for (int n = 0; n < 2; ++n) acc[a][b][m][n] = (f32x4){0.f, 0.f, 0.f, 0.f};
;         }
;         cur = nxt; cA = nA; cB = nB; ++ui;
;         if constexpr (ALIGN_EPI) { if (wr == 1) PG8_BAR; }
;     __device__ __forceinline__ void operator()(const f32x4 (&acc)[2][2][4][2], const Unit& u, int wr, int wc, int fr, int fq) const {
;     ...
;                 const int r = row0 + ai * HALF + m * 16;
;                 bf16_t* rowp = H + (size_t)r * ldh + col0;
;                 f32x2 st = (f32x2){0.f, 1.f};
;                 if (rsum) st = ln_stats(*(const f32x2*)(rsum + 2 * (size_t)r));
;                 f32x4 v0, v1;
; #pragma unroll
;                 for (int j = 0; j < 4; ++j) {
;                     const float g0 = st[1] * (acc[ai][0][m][0][j] - st[0] * s1[0][0][j]) + s2[0][0][j], u0 = st[1] * (acc[ai][1][m][0][j] - st[0] * s1[1][0][j]) + s2[1][0][j];
;                     const float g1 = st[1] * (acc[ai][0][m][1][j] - st[0] * s1[0][1][j]) + s2[0][1][j], u1 = st[1] * (acc[ai][1][m][1][j] - st[0] * s1[1][1][j]) + s2[1][1][j];
;                     v0[j] = siluf_(g0) * u0; v1[j] = siluf_(g1) * u1;
;                 }
;                 u32x4 w; w.x = cvt_pk_bf16(v0[0], v0[1]); w.y = cvt_pk_bf16(v0[2], v0[3]); w.z = cvt_pk_bf16(v1[0], v1[1]); w.w = cvt_pk_bf16(v1[2], v1[3]);
;                 *(u32x4*)rowp = w;
	v_exp_f32_e32 v41, v41
	v_mul_f32_e32 v40, v52, v40
	v_mul_f32_e32 v45, 0xbfb8aa3b, v32
	v_add_f32_e32 v41, 1.0, v41
	v_rcp_f32_e32 v41, v41
	v_exp_f32_e32 v45, v45
	v_mul_f32_e32 v50, v40, v53
	v_mov_b32_e32 v40, v42
	v_mul_f32_e32 v36, v36, v41
	v_mul_f32_e32 v51, v36, v37
	v_mov_b32_e32 v36, v46
	v_mov_b32_e32 v37, v38
	v_add_f32_e32 v45, 1.0, v45
	v_mul_f32_e32 v38, 0xbfb8aa3b, v36
	v_exp_f32_e32 v38, v38
	v_mov_b32_e32 v41, v34
	v_rcp_f32_e32 v45, v45
	v_add_f32_e32 v34, 1.0, v38
	v_rcp_f32_e32 v34, v34
	v_mul_f32_e32 v38, 0xbfb8aa3b, v40
	v_exp_f32_e32 v38, v38
	v_mul_f32_e32 v32, v32, v45
	v_mul_f32_e32 v42, v32, v33
	v_mul_f32_e32 v32, v36, v34
	v_mul_f32_e32 v36, v32, v37
	v_add_f32_e32 v32, 1.0, v38
	v_mov_b32_e32 v38, v47
	v_rcp_f32_e32 v37, v32
	v_pk_add_f32 v[32:33], v[38:39], 0 op_sel_hi:[1,0]
	v_mov_b32_e32 v34, v43
	v_mul_f32_e32 v38, 0xbfb8aa3b, v32
	v_exp_f32_e32 v38, v38
	v_mul_f32_e32 v39, 0xbfb8aa3b, v34
	v_exp_f32_e32 v39, v39
	v_mul_f32_e32 v37, v40, v37
	v_add_f32_e32 v38, 1.0, v38
	v_rcp_f32_e32 v38, v38
	v_add_f32_e32 v39, 1.0, v39
	v_rcp_f32_e32 v39, v39
	v_mul_f32_e32 v37, v37, v41
	v_mul_f32_e32 v32, v32, v38
	v_mul_f32_e32 v33, v32, v33
	v_mul_f32_e32 v32, v34, v39
	v_mul_f32_e32 v35, v32, v35
	v_cvt_pk_bf16_f32 v32, v44, v51
	v_cvt_pk_bf16_f32 v33, v36, v33
	v_cvt_pk_bf16_f32 v34, v50, v42
	v_cvt_pk_bf16_f32 v35, v37, v35
	global_store_dwordx4 v[48:49], v[32:35], off
	v_mov_b32_e32 v36, v24
	v_mov_b32_e32 v37, v16
	v_mov_b32_e32 v34, v28
	v_mov_b32_e32 v35, v20
	v_mul_f32_e32 v20, 0xbfb8aa3b, v34
	v_exp_f32_e32 v20, v20
	v_add_u32_e32 v32, 0xa0, v150
	v_mad_i64_i32 v[32:33], s[20:21], v32, s51, v[142:143]
	v_add_f32_e32 v16, 1.0, v20
	v_rcp_f32_e32 v16, v16
	v_mul_f32_e32 v20, 0xbfb8aa3b, v36
	v_exp_f32_e32 v20, v20
	v_lshl_add_u64 v[32:33], v[32:33], 0, v[140:141]
	v_mul_f32_e32 v16, v34, v16
	v_mul_f32_e32 v28, v16, v35
	v_add_f32_e32 v16, 1.0, v20
	v_mov_b32_e32 v20, v29
	v_rcp_f32_e32 v24, v16
	v_mov_b32_e32 v16, v25
	v_mul_f32_e32 v25, 0xbfb8aa3b, v20
	v_exp_f32_e32 v25, v25
	v_mul_f32_e32 v24, v36, v24
	v_mul_f32_e32 v29, 0xbfb8aa3b, v16
	v_add_f32_e32 v25, 1.0, v25
	v_rcp_f32_e32 v25, v25
	v_exp_f32_e32 v29, v29
	v_mul_f32_e32 v34, v24, v37
	v_mov_b32_e32 v24, v26
	v_mul_f32_e32 v20, v20, v25
	v_mul_f32_e32 v35, v20, v21
	v_mov_b32_e32 v20, v30
	v_mov_b32_e32 v21, v22
	v_add_f32_e32 v29, 1.0, v29
	v_mul_f32_e32 v22, 0xbfb8aa3b, v20
	v_exp_f32_e32 v22, v22
	v_mov_b32_e32 v25, v18
	v_rcp_f32_e32 v29, v29
	v_add_f32_e32 v18, 1.0, v22
	v_rcp_f32_e32 v18, v18
	v_mul_f32_e32 v22, 0xbfb8aa3b, v24
	v_exp_f32_e32 v22, v22
	v_mul_f32_e32 v16, v16, v29
	v_mul_f32_e32 v26, v16, v17
	v_mul_f32_e32 v16, v20, v18
	v_mul_f32_e32 v20, v16, v21
	v_add_f32_e32 v16, 1.0, v22
	v_mov_b32_e32 v22, v31
	v_rcp_f32_e32 v21, v16
	v_pk_add_f32 v[16:17], v[22:23], 0 op_sel_hi:[1,0]
	v_mov_b32_e32 v18, v27
	v_mul_f32_e32 v22, 0xbfb8aa3b, v16
	v_exp_f32_e32 v22, v22
	v_mul_f32_e32 v23, 0xbfb8aa3b, v18
	v_exp_f32_e32 v23, v23
	v_mul_f32_e32 v21, v24, v21
	v_add_f32_e32 v22, 1.0, v22
	v_rcp_f32_e32 v22, v22
	v_add_f32_e32 v23, 1.0, v23
	v_rcp_f32_e32 v23, v23
	v_mul_f32_e32 v21, v21, v25
	v_mul_f32_e32 v16, v16, v22
	v_mul_f32_e32 v17, v16, v17
	v_mul_f32_e32 v16, v18, v23
	v_mul_f32_e32 v19, v16, v19
	v_cvt_pk_bf16_f32 v16, v28, v35
	v_cvt_pk_bf16_f32 v17, v20, v17
	v_cvt_pk_bf16_f32 v18, v34, v26
	v_cvt_pk_bf16_f32 v19, v21, v19
	global_store_dwordx4 v[32:33], v[16:19], off
	v_mov_b32_e32 v20, v8
	v_mov_b32_e32 v21, v0
	v_mov_b32_e32 v18, v12
	v_mov_b32_e32 v19, v4
	v_mul_f32_e32 v4, 0xbfb8aa3b, v18
	v_exp_f32_e32 v4, v4
	v_add_u32_e32 v16, 0xb0, v150
	v_mad_i64_i32 v[16:17], s[20:21], v16, s51, v[142:143]
	v_add_f32_e32 v0, 1.0, v4
	v_rcp_f32_e32 v0, v0
	v_mul_f32_e32 v4, 0xbfb8aa3b, v20
	v_exp_f32_e32 v4, v4
	v_lshl_add_u64 v[16:17], v[16:17], 0, v[140:141]
	v_mul_f32_e32 v0, v18, v0
	v_mul_f32_e32 v12, v0, v19
	v_add_f32_e32 v0, 1.0, v4
	v_mov_b32_e32 v4, v13
	v_rcp_f32_e32 v8, v0
	v_mov_b32_e32 v0, v9
	v_mul_f32_e32 v9, 0xbfb8aa3b, v4
	v_exp_f32_e32 v9, v9
	v_mul_f32_e32 v8, v20, v8
	v_mul_f32_e32 v13, 0xbfb8aa3b, v0
	v_add_f32_e32 v9, 1.0, v9
	v_rcp_f32_e32 v9, v9
	v_exp_f32_e32 v13, v13
	v_mul_f32_e32 v18, v8, v21
	v_mov_b32_e32 v8, v10
	v_mul_f32_e32 v4, v4, v9
	v_mul_f32_e32 v19, v4, v5
	v_mov_b32_e32 v4, v14
	v_mov_b32_e32 v5, v6
	v_add_f32_e32 v13, 1.0, v13
	v_mul_f32_e32 v6, 0xbfb8aa3b, v4
	v_exp_f32_e32 v6, v6
	v_mov_b32_e32 v9, v2
	v_rcp_f32_e32 v13, v13
	v_add_f32_e32 v2, 1.0, v6
	v_rcp_f32_e32 v2, v2
	v_mul_f32_e32 v6, 0xbfb8aa3b, v8
	v_exp_f32_e32 v6, v6
	v_mul_f32_e32 v0, v0, v13
	v_mul_f32_e32 v10, v0, v1
	v_mul_f32_e32 v0, v4, v2
	v_mul_f32_e32 v4, v0, v5
	v_add_f32_e32 v0, 1.0, v6
	v_mov_b32_e32 v6, v15
	v_rcp_f32_e32 v5, v0
	v_pk_add_f32 v[0:1], v[6:7], 0 op_sel_hi:[1,0]
	v_mov_b32_e32 v2, v11
	v_mul_f32_e32 v6, 0xbfb8aa3b, v0
	v_exp_f32_e32 v6, v6
	v_mul_f32_e32 v7, 0xbfb8aa3b, v2
	v_exp_f32_e32 v7, v7
	v_mul_f32_e32 v5, v8, v5
	v_add_f32_e32 v6, 1.0, v6
	v_rcp_f32_e32 v6, v6
	v_add_f32_e32 v7, 1.0, v7
	v_rcp_f32_e32 v7, v7
	s_andn2_b64 vcc, exec, s[10:11]
	v_mul_f32_e32 v0, v0, v6
	v_mul_f32_e32 v1, v0, v1
	v_mul_f32_e32 v0, v2, v7
	v_mul_f32_e32 v3, v0, v3
	s_mov_b64 s[10:11], -1
	v_mul_f32_e32 v5, v5, v9
	v_cvt_pk_bf16_f32 v0, v12, v19
	v_cvt_pk_bf16_f32 v1, v4, v1
	v_cvt_pk_bf16_f32 v2, v18, v10
	v_cvt_pk_bf16_f32 v3, v5, v3
	global_store_dwordx4 v[16:17], v[0:3], off
	s_cbranch_vccnz .LBB0_147
	s_andn2_b64 vcc, exec, s[0:1]
	s_cbranch_vccnz .LBB0_146
	s_barrier
	s_branch .LBB0_146
